# v48 + split-piece units keep their aligned seam (both halves drain the partial stores together); regular units staggered
# speedup vs baseline: 1.0054x; 1.0054x over previous
.Lpeel_done_2:
	v_readlane_b32 s44, v254, 27
	v_readlane_b32 s45, v254, 28
	s_cmp_gt_i32 s14, -1
	s_cselect_b64 s[100:101], -1, 0
	s_orn2_b64 s[98:99], s[100:101], s[40:41]
	s_and_b64 s[44:45], s[44:45], s[98:99]
	s_and_b64 vcc, exec, s[44:45]
	s_cbranch_vccz .LBB0_2028
	s_barrier
	s_cmp_lt_i32 s14, 0
	s_mov_b64 s[44:45], -1
	s_cbranch_scc1 .LBB0_2029

.LBB0_2047:
	v_readlane_b32 s4, v254, 58
	v_readlane_b32 s5, v254, 59
	s_and_b64 vcc, exec, s[4:5]
	s_cbranch_vccnz .LBB0_2005
	s_and_b64 vcc, exec, s[100:101]
	s_cbranch_vccz .LBB0_2005
	s_barrier
	s_branch .LBB0_2005

.Lpeel_done_3:
	v_readlane_b32 s44, v254, 27
	v_readlane_b32 s45, v254, 28
	s_cmp_gt_i32 s16, -1
	s_cselect_b64 s[100:101], -1, 0
	s_or_b64 s[98:99], s[100:101], s[10:11]
	s_and_b64 s[44:45], s[44:45], s[98:99]
	s_and_b64 vcc, exec, s[44:45]
	s_cbranch_vccz .LBB0_2297
	s_barrier
	s_cmp_lt_i32 s16, 0
	s_mov_b64 s[44:45], -1
	s_cbranch_scc1 .LBB0_2298

.LBB0_2300:
	v_readlane_b32 s10, v254, 58
	v_readlane_b32 s11, v254, 59
	s_and_b64 vcc, exec, s[10:11]
	s_cbranch_vccnz .LBB0_2270
	s_and_b64 vcc, exec, s[100:101]
	s_cbranch_vccz .LBB0_2270
	s_barrier
	s_branch .LBB0_2270

.Lpeel_done_4:
	v_readlane_b32 s44, v254, 27
	v_readlane_b32 s45, v254, 28
	s_cmp_gt_i32 s10, -1
	s_cselect_b64 s[100:101], -1, 0
	s_orn2_b64 s[98:99], s[100:101], s[38:39]
	s_and_b64 s[44:45], s[44:45], s[98:99]
	s_and_b64 vcc, exec, s[44:45]
	s_cbranch_vccz .LBB0_2461
	s_barrier
	s_cmp_lt_i32 s10, 0
	s_mov_b64 s[44:45], -1
	s_cbranch_scc1 .LBB0_2462

.LBB0_2464:
	v_readlane_b32 s38, v254, 58
	v_readlane_b32 s39, v254, 59
	s_and_b64 vcc, exec, s[38:39]
	s_cbranch_vccnz .LBB0_2438
	s_and_b64 vcc, exec, s[100:101]
	s_cbranch_vccz .LBB0_2438
	s_barrier
	s_branch .LBB0_2438
